# opt17
# speedup vs baseline: 1.0141x; 1.0019x over previous
; template <int K, bool HG>
; __device__ void chunk_item(const Ctx& cx, CParamsPtr pp, int l, int item, char* shm) {
;     ...
;   auto prefetch = [&](int c) {
;     const size_t t0 = tb + (size_t)c * C;
;     const u16* rowq = p.proj + t0 * NP + qcol;
;     const u16* rowk = p.proj + t0 * NP + kcol;
;     const float* rowg = p.gla_a + t0 * 1024 + hd * 256;
; #pragma unroll
;     for (int i = 0; i < TPS; ++i) {
;       typedef const __attribute__((address_space(1))) char* gcp;
;       rq[i] = *(const __attribute__((address_space(1))) u16*)((gcp)opq(rowq + (size_t)i * NP) + lo2);
;       rk[i] = *(const __attribute__((address_space(1))) u16*)((gcp)opq(rowk + (size_t)i * NP) + lo2);
;       if (!HG) rg[i] = *(const __attribute__((address_space(1))) float*)((gcp)opq(rowg + (size_t)i * 1024) + lo4);
;     }
;     ...
;         gi = rg[i];
;         kvv[i] = kraw;
;         qvv[i] = qraw * 0.0625f;
;       }
;       run += gi;
;       bl[i] = run;
;     }
.LBB0_202:
	s_and_b32 s12, s27, 0x10000
	s_add_i32 s28, s12, 0
	s_cmp_lg_u32 s14, 0xf80000
	s_cselect_b64 s[12:13], -1, 0
	s_cmp_lg_u64 s[12:13], 0
	s_addc_u32 s12, s22, 0
	s_lshl_b32 s12, s12, 5
	s_add_u32 s12, s16, s12
	s_addc_u32 s13, s17, 0
	s_mul_i32 s18, s13, 0xc000
	s_mul_hi_u32 s19, s12, 0xc000
	s_add_i32 s19, s19, s18
	s_mul_i32 s18, s12, 0xc000
	s_add_u32 s18, s25, s18
	s_addc_u32 s19, s26, s19
	s_add_u32 s30, s18, 0x800
	s_addc_u32 s31, s19, 0
	s_lshl_b64 s[20:21], s[12:13], 12
	s_mov_b64 s[34:35], s[18:19]
	s_add_u32 s20, s23, s20
	v_lshlrev_b32_e32 v0, 16, v123
	global_load_ushort v123, v112, s[34:35]
	s_addc_u32 s21, s24, s21
	v_add_f32_e32 v109, 0, v124
	global_load_ushort v179, v112, s[30:31]
	s_mov_b64 s[30:31], s[20:21]
	v_mul_f32_e32 v107, 0x3d800000, v0
	global_load_dword v124, v114, s[30:31]
	s_add_u32 s30, s18, 0xc000
	s_addc_u32 s31, s19, 0
	v_lshlrev_b32_e32 v0, 16, v125
	global_load_ushort v125, v112, s[30:31]
	s_add_u32 s30, s18, 0xc800
	s_addc_u32 s31, s19, 0
	v_add_f32_e32 v108, v126, v109
	global_load_ushort v180, v112, s[30:31]
	s_add_u32 s30, s20, 0x1000
	s_addc_u32 s31, s21, 0
	v_mul_f32_e32 v106, 0x3d800000, v0
	global_load_dword v126, v114, s[30:31]
	s_add_u32 s30, s18, 0x18000
	s_addc_u32 s31, s19, 0
	v_lshlrev_b32_e32 v0, 16, v127
	global_load_ushort v127, v112, s[30:31]
	s_add_u32 s30, s18, 0x18800
	s_addc_u32 s31, s19, 0
	v_add_f32_e32 v105, v132, v108
	global_load_ushort v181, v112, s[30:31]
	s_add_u32 s30, s20, 0x2000
	s_addc_u32 s31, s21, 0
	v_mul_f32_e32 v103, 0x3d800000, v0
	global_load_dword v132, v114, s[30:31]
	s_add_u32 s30, s18, 0x24000
	s_addc_u32 s31, s19, 0
	v_lshlrev_b32_e32 v0, 16, v133
	global_load_ushort v133, v112, s[30:31]
	s_add_u32 s30, s18, 0x24800
	s_addc_u32 s31, s19, 0
	v_add_f32_e32 v104, v134, v105
	global_load_ushort v182, v112, s[30:31]
	s_add_u32 s30, s20, 0x3000
	s_addc_u32 s31, s21, 0
	v_mul_f32_e32 v102, 0x3d800000, v0
	global_load_dword v134, v114, s[30:31]
	s_add_u32 s30, s18, 0x30000
	s_addc_u32 s31, s19, 0
	v_lshlrev_b32_e32 v0, 16, v135
	global_load_ushort v135, v112, s[30:31]
	s_add_u32 s30, s18, 0x30800
	s_addc_u32 s31, s19, 0
	v_add_f32_e32 v101, v136, v104
	global_load_ushort v183, v112, s[30:31]
	s_add_u32 s30, s20, 0x4000
	s_addc_u32 s31, s21, 0
	v_mul_f32_e32 v99, 0x3d800000, v0
	global_load_dword v136, v114, s[30:31]
	s_add_u32 s30, s18, 0x3c000
	s_addc_u32 s31, s19, 0
	v_lshlrev_b32_e32 v0, 16, v137
	global_load_ushort v137, v112, s[30:31]
	s_add_u32 s30, s18, 0x3c800
	s_addc_u32 s31, s19, 0
	v_add_f32_e32 v100, v139, v101
	global_load_ushort v184, v112, s[30:31]
	s_add_u32 s30, s20, 0x5000
	s_addc_u32 s31, s21, 0
	v_mul_f32_e32 v98, 0x3d800000, v0
	global_load_dword v139, v114, s[30:31]
	s_add_u32 s30, s18, 0x48000
	s_addc_u32 s31, s19, 0
	v_lshlrev_b32_e32 v0, 16, v141
	global_load_ushort v141, v112, s[30:31]
	s_add_u32 s30, s18, 0x48800
	s_addc_u32 s31, s19, 0
	v_add_f32_e32 v97, v144, v100
	global_load_ushort v185, v112, s[30:31]
	s_add_u32 s30, s20, 0x6000
	s_addc_u32 s31, s21, 0
	v_mul_f32_e32 v95, 0x3d800000, v0
	global_load_dword v144, v114, s[30:31]
	s_add_u32 s30, s18, 0x54000
	s_addc_u32 s31, s19, 0
	v_lshlrev_b32_e32 v0, 16, v146
	global_load_ushort v146, v112, s[30:31]
	s_add_u32 s30, s18, 0x54800
	s_addc_u32 s31, s19, 0
	v_add_f32_e32 v96, v147, v97
	global_load_ushort v186, v112, s[30:31]
	s_add_u32 s30, s20, 0x7000
	s_addc_u32 s31, s21, 0
	v_mul_f32_e32 v94, 0x3d800000, v0
	global_load_dword v147, v114, s[30:31]
	s_add_u32 s30, s18, 0x60000
	s_addc_u32 s31, s19, 0
	v_lshlrev_b32_e32 v0, 16, v148
	global_load_ushort v148, v112, s[30:31]
	s_add_u32 s30, s18, 0x60800
	s_addc_u32 s31, s19, 0
	v_add_f32_e32 v93, v149, v96
	global_load_ushort v187, v112, s[30:31]
	s_add_u32 s30, s20, 0x8000
	s_addc_u32 s31, s21, 0
	v_mul_f32_e32 v91, 0x3d800000, v0
	global_load_dword v149, v114, s[30:31]
	s_add_u32 s30, s18, 0x6c000
	s_addc_u32 s31, s19, 0
	v_lshlrev_b32_e32 v0, 16, v150
	global_load_ushort v150, v112, s[30:31]
	s_add_u32 s30, s18, 0x6c800
	s_addc_u32 s31, s19, 0
	v_add_f32_e32 v92, v151, v93
	global_load_ushort v188, v112, s[30:31]
	s_add_u32 s30, s20, 0x9000
	s_addc_u32 s31, s21, 0
	v_mul_f32_e32 v90, 0x3d800000, v0
	global_load_dword v151, v114, s[30:31]
	s_add_u32 s30, s18, 0x78000
	s_addc_u32 s31, s19, 0
	v_lshlrev_b32_e32 v0, 16, v152
	global_load_ushort v152, v112, s[30:31]
	s_add_u32 s30, s18, 0x78800
	s_addc_u32 s31, s19, 0
	v_add_f32_e32 v89, v153, v92
	global_load_ushort v189, v112, s[30:31]
	s_add_u32 s30, s20, 0xa000
	s_addc_u32 s31, s21, 0
	v_mul_f32_e32 v87, 0x3d800000, v0
	global_load_dword v153, v114, s[30:31]
	s_add_u32 s30, s18, 0x84000
	s_addc_u32 s31, s19, 0
	v_lshlrev_b32_e32 v0, 16, v154
	global_load_ushort v154, v112, s[30:31]
	s_add_u32 s30, s18, 0x84800
	s_addc_u32 s31, s19, 0
	v_add_f32_e32 v88, v156, v89
	global_load_ushort v190, v112, s[30:31]
	s_add_u32 s30, s20, 0xb000
	s_addc_u32 s31, s21, 0
	v_mul_f32_e32 v86, 0x3d800000, v0
	global_load_dword v156, v114, s[30:31]
	s_add_u32 s30, s18, 0x90000
	s_addc_u32 s31, s19, 0
	v_lshlrev_b32_e32 v0, 16, v157
	global_load_ushort v157, v112, s[30:31]
	s_add_u32 s30, s18, 0x90800
	s_addc_u32 s31, s19, 0
	v_add_f32_e32 v85, v160, v88
	global_load_ushort v191, v112, s[30:31]
	s_add_u32 s30, s20, 0xc000
	s_addc_u32 s31, s21, 0
	v_mul_f32_e32 v83, 0x3d800000, v0
	global_load_dword v160, v114, s[30:31]
	s_add_u32 s30, s18, 0x9c000
	s_addc_u32 s31, s19, 0
	v_lshlrev_b32_e32 v0, 16, v168
	global_load_ushort v168, v112, s[30:31]
	s_add_u32 s30, s18, 0x9c800
	s_addc_u32 s31, s19, 0
	v_add_f32_e32 v84, v172, v85
	global_load_ushort v192, v112, s[30:31]
	s_add_u32 s30, s20, 0xd000
	s_addc_u32 s31, s21, 0
	v_mul_f32_e32 v82, 0x3d800000, v0
	global_load_dword v172, v114, s[30:31]
	s_add_u32 s30, s18, 0xa8000
	s_addc_u32 s31, s19, 0
	v_lshlrev_b32_e32 v0, 16, v174
	global_load_ushort v174, v112, s[30:31]
	s_add_u32 s30, s18, 0xa8800
	s_addc_u32 s31, s19, 0
	v_add_f32_e32 v81, v175, v84
	v_lshl_add_u64 v[110:111], s[30:31], 0, v[112:113]
	s_add_u32 s30, s20, 0xe000
	s_addc_u32 s31, s21, 0
	v_mul_f32_e32 v79, 0x3d800000, v0
	v_lshlrev_b32_e32 v0, 16, v177
	s_waitcnt vmcnt(44)
; template <int K, bool HG>
; __device__ void chunk_item(const Ctx& cx, CParamsPtr pp, int l, int item, char* shm) {
;     ...
;     for (int j = 0; j < NSEG; ++j) {
;       const float rj = shi(run, (lane % LPS) + LPS * j);
;       total += rj;
;       if (j < seg) offs += rj;
;     }
;     uint32_t kpw[TPS / 2];
;     float kpv[TPS];
;     const float etot = __expf(total);
; #pragma unroll
;     for (int i = 0; i < TPS; ++i) {
;       const float bb = offs + bl[i];
;       const int t = seg * TPS + i;
;       const float eq = __expf(bb), ek = __expf(fminf(-bb, 85.0f)), ekp = etot * ek;
;       *(u16*)(QT + t * RS + kc * 2) = f2b(qvv[i] * eq);
;       *(u16*)(KT + t * RS + kc * 2) = f2b(kvv[i] * ek);
;       kpv[i] = kvv[i] * ekp;
	v_add_f32_e32 v80, v178, v81
	global_load_ushort v193, v[110:111], off
	v_mul_f32_e32 v2, 0x3d800000, v0
	v_lshl_add_u64 v[110:111], s[30:31], 0, v[114:115]
	s_add_u32 s30, s18, 0xb4000
	ds_bpermute_b32 v0, v143, v80
	s_addc_u32 s31, s19, 0
	s_add_u32 s18, s18, 0xb4800
	global_load_dword v175, v[110:111], off
	s_addc_u32 s19, s19, 0
	global_load_ushort v177, v112, s[30:31]
	s_waitcnt lgkmcnt(0)
	v_add_f32_e32 v0, 0, v0
	global_load_ushort v194, v112, s[18:19]
	s_add_u32 s18, s20, 0xf000
	s_addc_u32 s19, s21, 0
	v_cndmask_b32_e64 v196, v0, 0, vcc
	v_add_f32_e32 v109, v109, v196
	global_load_dword v178, v114, s[18:19]
	v_mul_f32_e32 v110, 0x3fb8aa3b, v109
	v_max_f32_e32 v109, 0xc2f54216, v110
	ds_bpermute_b32 v195, v169, v80
	v_exp_f32_e32 v111, v110
	v_exp_f32_e64 v110, -v109
	v_mul_f32_e32 v107, v107, v111
	s_waitcnt lgkmcnt(0)
	v_add_f32_e32 v0, v0, v195
	v_cvt_pk_bf16_f32 v107, v107, s0
	v_add3_u32 v195, s28, v122, v145
	ds_write_b16 v195, v107
	v_add_f32_e32 v107, v108, v196
	v_mul_f32_e32 v108, 0x3fb8aa3b, v107
	v_max_f32_e32 v107, 0xc2f54216, v108
	v_exp_f32_e32 v108, v108
	v_exp_f32_e64 v111, -v107
	v_mul_f32_e32 v106, v106, v108
	v_cvt_pk_bf16_f32 v106, v106, s0
	ds_write_b16 v195, v106 offset:528
	v_lshlrev_b32_e32 v106, 16, v78
	v_and_b32_e32 v107, 0xffff0000, v78
	v_mul_f32_e32 v78, v110, v106
	v_cvt_pk_bf16_f32 v78, v78, s0
	ds_write_b16 v195, v78 offset:16896
	v_mul_f32_e32 v78, v111, v107
	v_cvt_pk_bf16_f32 v78, v78, s0
	v_mul_f32_e32 v0, 0x3fb8aa3b, v0
	ds_write_b16 v195, v78 offset:17424
	v_add_f32_e32 v78, v105, v196
	v_exp_f32_e32 v0, v0
	v_mul_f32_e32 v105, 0x3fb8aa3b, v78
	v_max_f32_e32 v78, 0xc2f54216, v105
	v_exp_f32_e32 v105, v105
	v_pk_mul_f32 v[108:109], v[0:1], v[110:111] op_sel_hi:[0,1]
	v_pk_mul_f32 v[106:107], v[108:109], v[106:107]
	v_exp_f32_e64 v108, -v78
	v_mul_f32_e32 v78, v103, v105
	v_cvt_pk_bf16_f32 v78, v78, s0
	ds_write_b16 v195, v78 offset:1056
	v_add_f32_e32 v78, v104, v196
	v_mul_f32_e32 v103, 0x3fb8aa3b, v78
	v_max_f32_e32 v78, 0xc2f54216, v103
	v_exp_f32_e32 v103, v103
	v_exp_f32_e64 v109, -v78
	v_mul_f32_e32 v78, v102, v103
	v_lshlrev_b32_e32 v102, 16, v77
	v_and_b32_e32 v103, 0xffff0000, v77
	v_mul_f32_e32 v77, v108, v102
	v_cvt_pk_bf16_f32 v77, v77, s0
	ds_write_b16 v195, v77 offset:17952
	v_mul_f32_e32 v77, v109, v103
	v_cvt_pk_bf16_f32 v77, v77, s0
	v_cvt_pk_bf16_f32 v78, v78, s0
	ds_write_b16 v195, v77 offset:18480
	v_add_f32_e32 v77, v101, v196
	ds_write_b16 v195, v78 offset:1584
	v_mul_f32_e32 v78, 0x3fb8aa3b, v77
	v_max_f32_e32 v77, 0xc2f54216, v78
	v_exp_f32_e32 v78, v78
	v_pk_mul_f32 v[104:105], v[0:1], v[108:109] op_sel_hi:[0,1]
	v_pk_mul_f32 v[102:103], v[104:105], v[102:103]
	v_exp_f32_e64 v104, -v77
	v_mul_f32_e32 v77, v99, v78
	v_cvt_pk_bf16_f32 v77, v77, s0
	ds_write_b16 v195, v77 offset:2112
	v_add_f32_e32 v77, v100, v196
	v_mul_f32_e32 v78, 0x3fb8aa3b, v77
	v_max_f32_e32 v77, 0xc2f54216, v78
	v_exp_f32_e32 v78, v78
	v_exp_f32_e64 v105, -v77
	v_mul_f32_e32 v77, v98, v78
	v_cvt_pk_bf16_f32 v77, v77, s0
	ds_write_b16 v195, v77 offset:2640
	v_and_b32_e32 v77, 0xffff0000, v76
	v_lshlrev_b32_e32 v76, 16, v76
	v_mul_f32_e32 v78, v104, v76
	v_cvt_pk_bf16_f32 v78, v78, s0
	ds_write_b16 v195, v78 offset:19008
	v_mul_f32_e32 v78, v105, v77
	v_cvt_pk_bf16_f32 v78, v78, s0
	ds_write_b16 v195, v78 offset:19536
	v_add_f32_e32 v78, v97, v196
	v_mul_f32_e32 v97, 0x3fb8aa3b, v78
	v_max_f32_e32 v78, 0xc2f54216, v97
	v_exp_f32_e32 v97, v97
	v_pk_mul_f32 v[98:99], v[0:1], v[104:105] op_sel_hi:[0,1]
	v_pk_mul_f32 v[76:77], v[98:99], v[76:77]
	v_exp_f32_e64 v98, -v78
	v_mul_f32_e32 v78, v95, v97
	v_cvt_pk_bf16_f32 v78, v78, s0
	ds_write_b16 v195, v78 offset:3168
	v_add_f32_e32 v78, v96, v196
	v_mul_f32_e32 v95, 0x3fb8aa3b, v78
	v_max_f32_e32 v78, 0xc2f54216, v95
	v_exp_f32_e32 v95, v95
	v_exp_f32_e64 v99, -v78
	v_mul_f32_e32 v78, v94, v95
	v_lshlrev_b32_e32 v94, 16, v75
	v_and_b32_e32 v95, 0xffff0000, v75
	v_mul_f32_e32 v75, v98, v94
	v_cvt_pk_bf16_f32 v75, v75, s0
	ds_write_b16 v195, v75 offset:20064
	v_mul_f32_e32 v75, v99, v95
	v_cvt_pk_bf16_f32 v75, v75, s0
	v_cvt_pk_bf16_f32 v78, v78, s0
	ds_write_b16 v195, v75 offset:20592
; template <int K, bool HG>
; __device__ void chunk_item(const Ctx& cx, CParamsPtr pp, int l, int item, char* shm) {
;     ...
; #pragma unroll
;     for (int i = 0; i < TPS; ++i) {
;       const float bb = offs + bl[i];
;       const int t = seg * TPS + i;
;       const float eq = __expf(bb), ek = __expf(fminf(-bb, 85.0f)), ekp = etot * ek;
;       *(u16*)(QT + t * RS + kc * 2) = f2b(qvv[i] * eq);
;       *(u16*)(KT + t * RS + kc * 2) = f2b(kvv[i] * ek);
;       kpv[i] = kvv[i] * ekp;
;     }
; #pragma unroll
;     for (int i = 0; i < TPS / 2; ++i) kpw[i] = pack2(kpv[2 * i], kpv[2 * i + 1]);
; #pragma unroll
;     for (int i = 0; i < TPS / 8; ++i)
;       *(uint4*)(KP + kc * 80 + seg * TPS * 2 + i * 16) = make_uint4(kpw[i * 4], kpw[i * 4 + 1], kpw[i * 4 + 2], kpw[i * 4 + 3]);
;     if (seg == 0) EB[kc] = etot;
	v_add_f32_e32 v75, v93, v196
	ds_write_b16 v195, v78 offset:3696
	v_mul_f32_e32 v78, 0x3fb8aa3b, v75
	v_max_f32_e32 v75, 0xc2f54216, v78
	v_exp_f32_e32 v78, v78
	v_pk_mul_f32 v[96:97], v[0:1], v[98:99] op_sel_hi:[0,1]
	v_pk_mul_f32 v[94:95], v[96:97], v[94:95]
	v_exp_f32_e64 v96, -v75
	v_mul_f32_e32 v75, v91, v78
	v_cvt_pk_bf16_f32 v75, v75, s0
	ds_write_b16 v195, v75 offset:4224
	v_add_f32_e32 v75, v92, v196
	v_mul_f32_e32 v78, 0x3fb8aa3b, v75
	v_max_f32_e32 v75, 0xc2f54216, v78
	v_exp_f32_e32 v78, v78
	v_exp_f32_e64 v97, -v75
	v_mul_f32_e32 v75, v90, v78
	v_cvt_pk_bf16_f32 v75, v75, s0
	ds_write_b16 v195, v75 offset:4752
	v_and_b32_e32 v75, 0xffff0000, v74
	v_lshlrev_b32_e32 v74, 16, v74
	v_mul_f32_e32 v78, v96, v74
	v_pk_mul_f32 v[90:91], v[0:1], v[96:97] op_sel_hi:[0,1]
	v_cvt_pk_bf16_f32 v78, v78, s0
	v_pk_mul_f32 v[90:91], v[90:91], v[74:75]
	v_add_f32_e32 v74, v89, v196
	ds_write_b16 v195, v78 offset:21120
	v_mul_f32_e32 v78, v97, v75
	v_mul_f32_e32 v75, 0x3fb8aa3b, v74
	v_max_f32_e32 v74, 0xc2f54216, v75
	v_exp_f32_e32 v75, v75
	v_cvt_pk_bf16_f32 v78, v78, s0
	ds_write_b16 v195, v78 offset:21648
	v_mul_f32_e32 v75, v87, v75
	v_cvt_pk_bf16_f32 v75, v75, s0
	ds_write_b16 v195, v75 offset:5280
	v_add_f32_e32 v75, v88, v196
	v_mul_f32_e32 v78, 0x3fb8aa3b, v75
	v_max_f32_e32 v75, 0xc2f54216, v78
	v_exp_f32_e32 v78, v78
	v_exp_f32_e64 v74, -v74
	v_exp_f32_e64 v75, -v75
	v_mul_f32_e32 v78, v86, v78
	v_lshlrev_b32_e32 v86, 16, v73
	v_and_b32_e32 v87, 0xffff0000, v73
	v_mul_f32_e32 v73, v74, v86
	v_cvt_pk_bf16_f32 v73, v73, s0
	ds_write_b16 v195, v73 offset:22176
	v_mul_f32_e32 v73, v75, v87
	v_cvt_pk_bf16_f32 v73, v73, s0
	ds_write_b16 v195, v73 offset:22704
	v_add_f32_e32 v73, v85, v196
	v_pk_mul_f32 v[88:89], v[0:1], v[74:75] op_sel_hi:[0,1]
	v_mul_f32_e32 v74, 0x3fb8aa3b, v73
	v_max_f32_e32 v73, 0xc2f54216, v74
	v_exp_f32_e32 v75, v74
	v_exp_f32_e64 v74, -v73
	v_mul_f32_e32 v73, v83, v75
	v_cvt_pk_bf16_f32 v73, v73, s0
	ds_write_b16 v195, v73 offset:6336
	v_add_f32_e32 v73, v84, v196
	v_cvt_pk_bf16_f32 v78, v78, s0
	v_mul_f32_e32 v75, 0x3fb8aa3b, v73
	v_max_f32_e32 v73, 0xc2f54216, v75
	ds_write_b16 v195, v78 offset:5808
	v_exp_f32_e32 v78, v75
	v_exp_f32_e64 v75, -v73
	v_mul_f32_e32 v73, v82, v78
	v_cvt_pk_bf16_f32 v73, v73, s0
	ds_write_b16 v195, v73 offset:6864
	v_and_b32_e32 v73, 0xffff0000, v72
	v_lshlrev_b32_e32 v72, 16, v72
	v_pk_mul_f32 v[82:83], v[0:1], v[74:75] op_sel_hi:[0,1]
	v_mul_f32_e32 v78, v74, v72
	v_pk_mul_f32 v[82:83], v[82:83], v[72:73]
	v_add_f32_e32 v72, v81, v196
	v_mul_f32_e32 v74, v75, v73
	v_mul_f32_e32 v73, 0x3fb8aa3b, v72
	v_max_f32_e32 v72, 0xc2f54216, v73
	v_exp_f32_e32 v73, v73
	v_cvt_pk_bf16_f32 v74, v74, s0
	ds_write_b16 v195, v74 offset:23760
	v_mul_f32_e32 v73, v79, v73
	v_cvt_pk_bf16_f32 v73, v73, s0
	ds_write_b16 v195, v73 offset:7392
	v_add_f32_e32 v73, v80, v196
	v_mul_f32_e32 v74, 0x3fb8aa3b, v73
	v_max_f32_e32 v73, 0xc2f54216, v74
	v_exp_f32_e32 v74, v74
	v_exp_f32_e64 v72, -v72
	v_exp_f32_e64 v73, -v73
	v_mul_f32_e32 v2, v2, v74
	v_lshlrev_b32_e32 v74, 16, v1
	v_and_b32_e32 v75, 0xffff0000, v1
	v_mul_f32_e32 v1, v72, v74
	v_cvt_pk_bf16_f32 v78, v78, s0
	v_cvt_pk_bf16_f32 v1, v1, s0
	ds_write_b16 v195, v78 offset:23232
	ds_write_b16 v195, v1 offset:24288
	v_pk_mul_f32 v[78:79], v[0:1], v[72:73] op_sel_hi:[0,1]
	v_mul_f32_e32 v1, v73, v75
	v_cvt_pk_bf16_f32 v1, v1, s0
	v_cvt_pk_bf16_f32 v2, v2, s0
	ds_write_b16 v195, v1 offset:24816
	v_add_u32_e32 v1, s28, v158
	v_pk_mul_f32 v[86:87], v[88:89], v[86:87]
	ds_write_b16 v195, v2 offset:7920
	v_pk_mul_f32 v[80:81], v[78:79], v[74:75]
	v_cvt_pk_bf16_f32 v72, v106, v107
	v_cvt_pk_bf16_f32 v73, v102, v103
	v_cvt_pk_bf16_f32 v74, v76, v77
	v_cvt_pk_bf16_f32 v75, v94, v95
	v_add_u32_e32 v2, v1, v159
	v_cvt_pk_bf16_f32 v76, v90, v91
	v_cvt_pk_bf16_f32 v77, v86, v87
	v_cvt_pk_bf16_f32 v78, v82, v83
	v_cvt_pk_bf16_f32 v79, v80, v81
	ds_write_b128 v2, v[72:75] offset:33792
	ds_write_b128 v2, v[76:79] offset:33808
	s_and_saveexec_b64 s[18:19], vcc
	s_cbranch_execz .LBB0_201
	v_add_u32_e32 v1, v1, v161
	ds_write_b32 v1, v0 offset:64512
	s_branch .LBB0_201
